# strategy 7.4: per-segment setprio flips removed from GEMM K-loops, one static s_setprio 1 for waves 4-7 per GEMM phase (on top of v4)
# baseline (speedup 1.0000x reference)
; #define PG8_STAGE(bufoff, gbase, voff) do { _Pragma("unroll") for (int _i = 0; _i < 2; ++_i) \
;         __builtin_amdgcn_global_load_lds((const unsigned*)((const char*)(gbase) + (voff)[_i]), (PG8_LAS unsigned*)(lds + (bufoff) + ldsw + _i * 8192), 16, 0, 0); } while (0)
; #define PG8_BAR __builtin_amdgcn_s_barrier()
; template <class Epi, class Sched, bool ALIGN_EPI = false, bool SP2 = false>
; __device__ __forceinline__ void gemm_phase(PG8_LAS unsigned char* lds, const Gemm g, const Sched S, const Epi E) {
;     ...
;     const int tid = tid_o, wid = __builtin_amdgcn_readfirstlane(tid >> 6), lane = tid & 63, wr = wid >> 2, wc = wid & 3, fr = lane & 15, fq = lane >> 4;
;     const int K = g.K, nt = K / BK;
;     unsigned voffA[2], voffB[2];
; #pragma unroll
;     for (int i = 0; i < 2; ++i) { int R, C; stage_rc(tid * 16 + i * 8192, R, C); const int Rb = Epi::PERM ? ((R & ~31) + perm32(R & 31)) : R;
;         voffA[i] = (unsigned)(R * K + C) * 2u; voffB[i] = (unsigned)(Rb * K + C) * 2u; }
;     ...
;     const char* cA = (const char*)g.A + (size_t)cur.pm * tstep; const char* cB = (const char*)g.Bt + (size_t)cur.pn * tstep;
;     S.a_ready(cur);
;     if constexpr (SP2) {
;         PG8_STAGE(PG8_SB(0, 0), cB, voffB); PG8_STAGE(PG8_SB(0, 1), cB + hstep, voffB); PG8_STAGE(PG8_SA(0, 0), cA, voffA); PG8_STAGE(PG8_SA(0, 1), cA + hstep, voffA);
;         if (wr == 1) PG8_BAR;
.LBB0_183:
	s_xor_b64 s[0:1], s[6:7], -1
	v_writelane_b32 v255, s0, 53
	s_cmp_ge_i32 s20, s92
	s_nop 0
	v_writelane_b32 v255, s1, 54
	s_cselect_b64 s[0:1], -1, 0
	s_cmp_lt_i32 s20, s93
	s_cselect_b64 s[4:5], -1, 0
	s_and_b64 s[4:5], s[0:1], s[4:5]
	s_andn2_b64 vcc, exec, s[4:5]
	s_cbranch_vccnz .LBB0_200
	v_readlane_b32 s4, v253, 20
	v_mov_b32_e32 v0, v204
	v_mov_b32_e32 v2, v204
	v_readlane_b32 s5, v253, 21
	s_andn2_b64 vcc, exec, s[4:5]
	v_readfirstlane_b32 s4, v2
	s_cbranch_vccnz .LBB0_200
	v_lshlrev_b32_e32 v0, 4, v2
	v_add_u32_e32 v4, 0x2000, v0
	v_ashrrev_i32_e32 v3, 31, v4
	v_lshrrev_b32_e32 v3, 22, v3
	v_add_u32_e32 v3, v4, v3
	v_ashrrev_i32_e32 v3, 10, v3
	v_mul_i32_i24_e32 v5, 0x400, v3
	v_sub_u32_e32 v4, v4, v5
	v_lshrrev_b32_e32 v5, 4, v4
	v_bitop3_b32 v5, v5, v4, 32 bitop3:0x6c
	v_ashrrev_i32_e32 v4, 31, v5
	v_lshrrev_b32_e32 v4, 26, v4
	v_add_u32_e32 v6, v5, v4
	v_lshlrev_b32_e32 v7, 3, v3
	v_ashrrev_i32_e32 v4, 6, v6
	v_and_b32_e32 v7, -16, v7
	v_add_u32_e32 v7, v4, v7
	v_and_b32_e32 v8, 3, v4
	s_mov_b32 s15, 0xfffe0
	v_lshrrev_b32_e32 v9, 2, v7
	v_lshlrev_b32_e32 v10, 1, v7
	v_and_b32_e32 v6, 0xc0, v6
	v_and_or_b32 v8, v7, s15, v8
	v_and_b32_e32 v9, 4, v9
	v_and_b32_e32 v10, 24, v10
	v_sub_u32_e32 v5, v5, v6
	v_or3_b32 v8, v8, v9, v10
	v_lshlrev_b32_e32 v9, 5, v3
	v_ashrrev_i16_sdwa v5, v208, sext(v5) dst_sel:DWORD dst_unused:UNUSED_PAD src0_sel:DWORD src1_sel:BYTE_0
	v_and_b32_e32 v9, 32, v9
	v_bfe_i32 v5, v5, 0, 16
	v_add_lshl_u32 v6, v9, v5, 1
	s_waitcnt vmcnt(0)
	v_lshl_add_u32 v130, v8, 12, v6
	v_lshl_add_u32 v132, v7, 12, v6
	v_bfe_i32 v6, v2, 27, 1
	v_lshrrev_b32_e32 v6, 22, v6
	v_add_u32_e32 v6, v0, v6
	v_and_b32_e32 v6, 0xfffffc00, v6
	v_sub_u32_e32 v0, v0, v6
	v_lshrrev_b32_e32 v6, 4, v0
	v_ashrrev_i32_e32 v7, 31, v2
	v_bitop3_b32 v0, v6, v0, 32 bitop3:0x6c
	v_lshrrev_b32_e32 v7, 26, v7
	v_ashrrev_i32_e32 v6, 31, v0
	v_add_u32_e32 v7, v2, v7
	v_lshrrev_b32_e32 v6, 26, v6
	v_ashrrev_i32_e32 v7, 6, v7
	v_add_u32_e32 v8, v0, v6
	v_lshlrev_b32_e32 v9, 3, v7
	v_ashrrev_i32_e32 v6, 6, v8
	v_and_b32_e32 v9, -16, v9
	s_mul_i32 s5, s22, 0x4200000
	v_readlane_b32 s14, v253, 18
	v_add_u32_e32 v9, v6, v9
	s_add_u32 s66, s14, s5
	v_readlane_b32 s5, v253, 19
	v_and_b32_e32 v10, 3, v6
	v_lshrrev_b32_e32 v11, 2, v9
	v_lshlrev_b32_e32 v12, 1, v9
	v_and_b32_e32 v8, 0xc0, v8
	s_addc_u32 s67, s5, 0
	s_ashr_i32 s14, s4, 6
	v_and_or_b32 v10, v9, s15, v10
	v_and_b32_e32 v11, 4, v11
	v_and_b32_e32 v12, 24, v12
	v_sub_u32_e32 v0, v0, v8
	s_ashr_i32 s5, s4, 8
	s_lshl_b32 s74, s14, 10
	v_or3_b32 v10, v10, v11, v12
	v_lshlrev_b32_e32 v11, 5, v7
	v_ashrrev_i16_sdwa v0, v208, sext(v0) dst_sel:DWORD dst_unused:UNUSED_PAD src0_sel:DWORD src1_sel:BYTE_0
	v_readlane_b32 s24, v253, 41
	v_and_b32_e32 v11, 32, v11
	v_bfe_i32 v8, v0, 0, 16
	v_readlane_b32 s25, v253, 42
	s_add_u32 s58, s66, s24
	v_add_lshl_u32 v11, v11, v8, 1
	s_addc_u32 s59, s67, s25
	s_add_i32 s75, s74, 0
	v_lshl_add_u32 v0, v10, 12, v11
	s_add_i32 m0, s75, 0x10000
	v_lshl_add_u32 v134, v9, 12, v11
	global_load_lds_dwordx4 v0, s[58:59]
	s_add_i32 m0, s75, 0x12000
	s_add_u32 s24, s58, 0x80000
	global_load_lds_dwordx4 v130, s[58:59]
	s_addc_u32 s25, s59, 0
	s_add_i32 m0, s75, 0x14000
	s_add_i32 s21, s75, 0x2000
	global_load_lds_dwordx4 v0, s[24:25]
	s_add_i32 m0, s75, 0x16000
	s_add_i32 s47, s75, 0x4000
	global_load_lds_dwordx4 v130, s[24:25]
	v_readlane_b32 s24, v253, 45
	s_mov_b32 m0, s75
	v_readlane_b32 s25, v253, 46
	s_add_i32 s77, s75, 0x6000
	s_cmp_eq_u32 s5, 1
	s_cselect_b64 s[38:39], -1, 0
	s_cmp_lg_u32 s5, 1
	s_nop 0
	global_load_lds_dwordx4 v134, s[24:25]
	s_mov_b32 m0, s21
	s_nop 0
	global_load_lds_dwordx4 v132, s[24:25]
	v_readlane_b32 s24, v253, 47
	s_mov_b32 m0, s47
	v_readlane_b32 s25, v253, 48
	s_nop 4
	global_load_lds_dwordx4 v134, s[24:25]
	s_mov_b32 m0, s77
	s_nop 0
	global_load_lds_dwordx4 v132, s[24:25]
	s_cbranch_scc1 .LBB0_187
	s_barrier
	s_setprio 1

; #define PG8_WAIT_V(n) asm volatile("s_waitcnt vmcnt(" #n ")" ::: "memory")
; #define PG8_BAR __builtin_amdgcn_s_barrier()
; template <class Epi, class Sched, bool ALIGN_EPI = false, bool SP2 = false>
; __device__ __forceinline__ void gemm_phase(PG8_LAS unsigned char* lds, const Gemm g, const Sched S, const Epi E) {
;     ...
;     PG8_WAIT_V(0);
;     if constexpr (!ALIGN_EPI) { if (wr == 0) PG8_BAR; }
;     PG8_BAR;
.LBB0_199:
	s_waitcnt vmcnt(0)
	s_setprio 0
	s_barrier

; #define PG8_STAGE(bufoff, gbase, voff) do { _Pragma("unroll") for (int _i = 0; _i < 2; ++_i) \
;         __builtin_amdgcn_global_load_lds((const unsigned*)((const char*)(gbase) + (voff)[_i]), (PG8_LAS unsigned*)(lds + (bufoff) + ldsw + _i * 8192), 16, 0, 0); } while (0)
; #define PG8_BAR __builtin_amdgcn_s_barrier()
; template <class Epi, class Sched, bool ALIGN_EPI = false, bool SP2 = false>
; __device__ __forceinline__ void gemm_phase(PG8_LAS unsigned char* lds, const Gemm g, const Sched S, const Epi E) {
;     ...
;     const int tid = tid_o, wid = __builtin_amdgcn_readfirstlane(tid >> 6), lane = tid & 63, wr = wid >> 2, wc = wid & 3, fr = lane & 15, fq = lane >> 4;
;     const int K = g.K, nt = K / BK;
;     unsigned voffA[2], voffB[2];
; #pragma unroll
;     for (int i = 0; i < 2; ++i) { int R, C; stage_rc(tid * 16 + i * 8192, R, C); const int Rb = Epi::PERM ? ((R & ~31) + perm32(R & 31)) : R;
;         voffA[i] = (unsigned)(R * K + C) * 2u; voffB[i] = (unsigned)(Rb * K + C) * 2u; }
;     ...
;     const char* cA = (const char*)g.A + (size_t)cur.pm * tstep; const char* cB = (const char*)g.Bt + (size_t)cur.pn * tstep;
;     S.a_ready(cur);
;     if constexpr (SP2) {
;         PG8_STAGE(PG8_SB(0, 0), cB, voffB); PG8_STAGE(PG8_SB(0, 1), cB + hstep, voffB); PG8_STAGE(PG8_SA(0, 0), cA, voffA); PG8_STAGE(PG8_SA(0, 1), cA + hstep, voffA);
;         if (wr == 1) PG8_BAR;
.LBB0_254:
	s_cmp_ge_i32 s4, s92
	s_cselect_b64 s[38:39], -1, 0
	s_and_b64 s[0:1], s[38:39], s[36:37]
	s_andn2_b64 vcc, exec, s[0:1]
	s_cbranch_vccnz .LBB0_279
	v_readlane_b32 s0, v253, 22
	v_mov_b32_e32 v0, v204
	v_mov_b32_e32 v6, v204
	v_readlane_b32 s1, v253, 23
	s_andn2_b64 vcc, exec, s[0:1]
	v_readfirstlane_b32 s0, v6
	s_cbranch_vccnz .LBB0_279
	v_lshlrev_b32_e32 v0, 4, v6
	v_add_u32_e32 v2, 0x2000, v0
	v_ashrrev_i32_e32 v3, 31, v2
	v_lshrrev_b32_e32 v3, 22, v3
	v_add_u32_e32 v3, v2, v3
	v_ashrrev_i32_e32 v7, 10, v3
	v_mul_i32_i24_e32 v3, 0x400, v7
	v_sub_u32_e32 v2, v2, v3
	v_lshrrev_b32_e32 v3, 4, v2
	v_bitop3_b32 v2, v3, v2, 32 bitop3:0x6c
	v_ashrrev_i32_e32 v3, 31, v2
	v_lshrrev_b32_e32 v3, 26, v3
	v_add_u32_e32 v3, v2, v3
	v_ashrrev_i32_e32 v8, 6, v3
	v_and_b32_e32 v3, 0xc0, v3
	v_sub_u32_e32 v2, v2, v3
	v_ashrrev_i16_sdwa v2, v208, sext(v2) dst_sel:DWORD dst_unused:UNUSED_PAD src0_sel:DWORD src1_sel:BYTE_0
	v_bfe_i32 v10, v2, 0, 16
	v_bfe_i32 v2, v6, 27, 1
	v_lshrrev_b32_e32 v2, 22, v2
	v_add_u32_e32 v2, v0, v2
	v_and_b32_e32 v2, 0xfffffc00, v2
	v_sub_u32_e32 v0, v0, v2
	v_lshrrev_b32_e32 v2, 4, v0
	v_ashrrev_i32_e32 v3, 31, v6
	v_bitop3_b32 v0, v2, v0, 32 bitop3:0x6c
	v_lshrrev_b32_e32 v3, 26, v3
	s_mul_i32 s22, s22, 0x4200000
	v_lshlrev_b32_e32 v4, 3, v7
	v_ashrrev_i32_e32 v2, 31, v0
	v_add_u32_e32 v3, v6, v3
	s_add_u32 s1, s90, s22
	v_and_b32_e32 v4, 0x7ffff0, v4
	v_lshrrev_b32_e32 v2, 26, v2
	v_ashrrev_i32_e32 v12, 6, v3
	s_addc_u32 s4, s91, 0
	v_add_u32_e32 v4, v8, v4
	s_movk_i32 s5, 0x1600
	v_lshlrev_b32_e32 v5, 5, v7
	v_add_u32_e32 v2, v0, v2
	v_lshlrev_b32_e32 v3, 3, v12
	s_add_u32 s16, s1, 0x2d00000
	v_mul_lo_u32 v4, v4, s5
	v_and_b32_e32 v9, 32, v5
	v_ashrrev_i32_e32 v11, 6, v2
	v_and_b32_e32 v3, 0x7ffff0, v3
	s_addc_u32 s21, s4, 0
	s_ashr_i32 s4, s0, 6
	v_or_b32_e32 v4, v4, v9
	v_add_u32_e32 v3, v11, v3
	v_and_b32_e32 v2, 0xc0, v2
	v_readlane_b32 s14, v253, 49
	s_ashr_i32 s1, s0, 8
	s_lshl_b32 s22, s4, 10
	s_waitcnt vmcnt(0)
	v_add_lshl_u32 v130, v4, v10, 1
	v_mul_lo_u32 v3, v3, s5
	v_lshlrev_b32_e32 v4, 5, v12
	v_sub_u32_e32 v0, v0, v2
	s_mul_i32 s5, s14, 0x2c0000
	v_and_b32_e32 v13, 32, v4
	v_ashrrev_i16_sdwa v0, v208, sext(v0) dst_sel:DWORD dst_unused:UNUSED_PAD src0_sel:DWORD src1_sel:BYTE_0
	s_add_u32 s52, s16, s5
	s_mul_hi_i32 s5, s14, 0x2c0000
	v_or_b32_e32 v3, v3, v13
	v_bfe_i32 v14, v0, 0, 16
	s_addc_u32 s53, s21, s5
	s_add_i32 s47, s22, 0
	v_add_lshl_u32 v0, v3, v14, 1
	s_add_i32 m0, s47, 0x10000
	v_mov_b32_e32 v131, v1
	global_load_lds_dwordx4 v0, s[52:53]
	s_add_i32 m0, s47, 0x12000
	s_add_u32 s14, s52, 0x160000
	global_load_lds_dwordx4 v130, s[52:53]
	s_addc_u32 s15, s53, 0
	s_add_i32 m0, s47, 0x14000
	s_add_i32 s62, s47, 0x2000
	global_load_lds_dwordx4 v0, s[14:15]
	s_add_i32 m0, s47, 0x16000
	s_add_i32 s63, s47, 0x4000
	global_load_lds_dwordx4 v130, s[14:15]
	v_readlane_b32 s14, v253, 50
	s_mov_b32 m0, s47
	v_readlane_b32 s15, v253, 51
	s_add_i32 s64, s47, 0x6000
	s_cmp_eq_u32 s1, 1
	s_mov_b64 s[30:31], s[82:83]
	s_mov_b64 s[26:27], s[80:81]
	v_lshl_add_u64 v[2:3], s[52:53], 0, v[0:1]
	global_load_lds_dwordx4 v0, s[14:15]
	s_mov_b32 m0, s62
	s_cselect_b64 s[40:41], -1, 0
	global_load_lds_dwordx4 v130, s[14:15]
	v_readlane_b32 s14, v253, 52
	s_mov_b32 m0, s63
	v_readlane_b32 s15, v253, 53
	s_cmp_lg_u32 s1, 1
	v_lshl_add_u64 v[4:5], s[52:53], 0, v[130:131]
	s_nop 2
	global_load_lds_dwordx4 v0, s[14:15]
	s_mov_b32 m0, s64
	s_nop 0
	global_load_lds_dwordx4 v130, s[14:15]
	s_cbranch_scc1 .LBB0_258
	s_barrier
	s_setprio 1

; #define PG8_STAGE(bufoff, gbase, voff) do { _Pragma("unroll") for (int _i = 0; _i < 2; ++_i) \
;         __builtin_amdgcn_global_load_lds((const unsigned*)((const char*)(gbase) + (voff)[_i]), (PG8_LAS unsigned*)(lds + (bufoff) + ldsw + _i * 8192), 16, 0, 0); } while (0)
; #define PG8_BAR __builtin_amdgcn_s_barrier()
; template <class Epi, class Sched, bool ALIGN_EPI = false, bool SP2 = false>
; __device__ __forceinline__ void gemm_phase(PG8_LAS unsigned char* lds, const Gemm g, const Sched S, const Epi E) {
;     ...
;     const int tid = tid_o, wid = __builtin_amdgcn_readfirstlane(tid >> 6), lane = tid & 63, wr = wid >> 2, wc = wid & 3, fr = lane & 15, fq = lane >> 4;
;     const int K = g.K, nt = K / BK;
;     unsigned voffA[2], voffB[2];
; #pragma unroll
;     for (int i = 0; i < 2; ++i) { int R, C; stage_rc(tid * 16 + i * 8192, R, C); const int Rb = Epi::PERM ? ((R & ~31) + perm32(R & 31)) : R;
;         voffA[i] = (unsigned)(R * K + C) * 2u; voffB[i] = (unsigned)(Rb * K + C) * 2u; }
;     ...
;     const char* cA = (const char*)g.A + (size_t)cur.pm * tstep; const char* cB = (const char*)g.Bt + (size_t)cur.pn * tstep;
;     S.a_ready(cur);
;     if constexpr (SP2) {
;         PG8_STAGE(PG8_SB(0, 0), cB, voffB); PG8_STAGE(PG8_SB(0, 1), cB + hstep, voffB); PG8_STAGE(PG8_SA(0, 0), cA, voffA); PG8_STAGE(PG8_SA(0, 1), cA + hstep, voffA);
;         if (wr == 1) PG8_BAR;
.LBB0_393:
	s_cmp_ge_i32 s4, s92
	s_cselect_b64 s[50:51], -1, 0
	s_and_b64 s[0:1], s[50:51], s[0:1]
	v_readlane_b32 s4, v255, 46
	v_readlane_b32 s5, v255, 47
	v_cndmask_b32_e64 v0, 0, 1, s[0:1]
	s_and_b64 vcc, exec, s[4:5]
	v_cmp_ne_u32_e64 s[38:39], 1, v0
	s_cbranch_vccz .LBB0_446
	s_and_b64 vcc, exec, s[38:39]
	s_cbranch_vccnz .LBB0_448
	v_readlane_b32 s0, v253, 24
	v_mov_b32_e32 v0, v204
	v_mov_b32_e32 v5, v204
	v_readlane_b32 s1, v253, 25
	s_andn2_b64 vcc, exec, s[0:1]
	v_readfirstlane_b32 s0, v5
	s_cbranch_vccnz .LBB0_448
	v_lshlrev_b32_e32 v0, 4, v5
	v_add_u32_e32 v3, 0x2000, v0
	v_ashrrev_i32_e32 v2, 31, v3
	v_lshrrev_b32_e32 v2, 22, v2
	v_add_u32_e32 v2, v3, v2
	v_ashrrev_i32_e32 v2, 10, v2
	v_mul_i32_i24_e32 v4, 0x400, v2
	v_sub_u32_e32 v3, v3, v4
	v_lshrrev_b32_e32 v4, 4, v3
	v_bitop3_b32 v4, v4, v3, 32 bitop3:0x6c
	v_ashrrev_i32_e32 v3, 31, v4
	v_lshrrev_b32_e32 v3, 26, v3
	v_add_u32_e32 v6, v4, v3
	v_lshlrev_b32_e32 v7, 3, v2
	v_ashrrev_i32_e32 v3, 6, v6
	v_and_b32_e32 v7, -16, v7
	v_add_u32_e32 v7, v3, v7
	v_and_b32_e32 v8, 3, v3
	s_mov_b32 s4, 0xfffe0
	v_lshrrev_b32_e32 v9, 2, v7
	v_lshlrev_b32_e32 v10, 1, v7
	v_and_b32_e32 v6, 0xc0, v6
	v_and_or_b32 v8, v7, s4, v8
	v_and_b32_e32 v9, 4, v9
	v_and_b32_e32 v10, 24, v10
	v_sub_u32_e32 v4, v4, v6
	v_or3_b32 v8, v8, v9, v10
	v_lshlrev_b32_e32 v9, 5, v2
	v_ashrrev_i16_sdwa v4, v208, sext(v4) dst_sel:DWORD dst_unused:UNUSED_PAD src0_sel:DWORD src1_sel:BYTE_0
	v_and_b32_e32 v9, 32, v9
	v_bfe_i32 v4, v4, 0, 16
	v_add_lshl_u32 v6, v9, v4, 1
	v_lshl_add_u32 v138, v8, 12, v6
	v_lshl_add_u32 v140, v7, 12, v6
	v_bfe_i32 v6, v5, 27, 1
	v_lshrrev_b32_e32 v6, 22, v6
	v_add_u32_e32 v6, v0, v6
	v_and_b32_e32 v6, 0xfffffc00, v6
	v_sub_u32_e32 v0, v0, v6
	v_lshrrev_b32_e32 v6, 4, v0
	v_ashrrev_i32_e32 v7, 31, v5
	v_bitop3_b32 v0, v6, v0, 32 bitop3:0x6c
	v_lshrrev_b32_e32 v7, 26, v7
	v_ashrrev_i32_e32 v6, 31, v0
	v_add_u32_e32 v7, v5, v7
	v_lshrrev_b32_e32 v6, 26, v6
	v_ashrrev_i32_e32 v7, 6, v7
	v_add_u32_e32 v8, v0, v6
	v_lshlrev_b32_e32 v9, 3, v7
	v_ashrrev_i32_e32 v6, 6, v8
	v_and_b32_e32 v9, -16, v9
	v_add_u32_e32 v9, v6, v9
	v_and_b32_e32 v10, 3, v6
	v_lshrrev_b32_e32 v11, 2, v9
	v_lshlrev_b32_e32 v12, 1, v9
	v_and_b32_e32 v8, 0xc0, v8
	v_and_or_b32 v10, v9, s4, v10
	v_and_b32_e32 v11, 4, v11
	v_and_b32_e32 v12, 24, v12
	v_sub_u32_e32 v0, v0, v8
	s_ashr_i32 s1, s0, 6
	v_or3_b32 v10, v10, v11, v12
	v_lshlrev_b32_e32 v11, 5, v7
	v_ashrrev_i16_sdwa v0, v208, sext(v0) dst_sel:DWORD dst_unused:UNUSED_PAD src0_sel:DWORD src1_sel:BYTE_0
	s_lshl_b32 s16, s1, 10
	v_and_b32_e32 v11, 32, v11
	v_bfe_i32 v8, v0, 0, 16
	v_add_lshl_u32 v11, v11, v8, 1
	s_add_i32 s21, s16, 0
	v_readlane_b32 s4, v254, 32
	v_lshl_add_u32 v0, v10, 12, v11
	s_add_i32 m0, s21, 0x10000
	v_readlane_b32 s5, v254, 33
	v_lshl_add_u32 v142, v9, 12, v11
	s_add_i32 s22, s21, 0x2000
	s_add_i32 s47, s21, 0x4000
	s_add_i32 s62, s21, 0x6000
	s_nop 0
	global_load_lds_dwordx4 v0, s[4:5]
	s_add_i32 m0, s21, 0x12000
	s_nop 0
	global_load_lds_dwordx4 v138, s[4:5]
	v_readlane_b32 s4, v254, 26
	s_add_i32 m0, s21, 0x14000
	v_readlane_b32 s5, v254, 27
	s_nop 4
	global_load_lds_dwordx4 v0, s[4:5]
	s_add_i32 m0, s21, 0x16000
	s_nop 0
	global_load_lds_dwordx4 v138, s[4:5]
	v_readlane_b32 s4, v254, 28
	s_mov_b32 m0, s21
	v_readlane_b32 s5, v254, 29
	s_nop 4
	global_load_lds_dwordx4 v142, s[4:5]
	s_mov_b32 m0, s22
	s_nop 0
	global_load_lds_dwordx4 v140, s[4:5]
	v_readlane_b32 s4, v254, 30
	s_mov_b32 m0, s47
	v_readlane_b32 s5, v254, 31
	s_nop 4
	global_load_lds_dwordx4 v142, s[4:5]
	s_mov_b32 m0, s62
	s_nop 0
	global_load_lds_dwordx4 v140, s[4:5]
	s_ashr_i32 s4, s0, 8
	s_cmp_eq_u32 s4, 1
	s_cselect_b64 s[6:7], -1, 0
	s_cmp_lg_u32 s4, 1
	s_cbranch_scc1 .LBB0_398
	s_barrier
	s_setprio 1

; #define PG8_STAGE(bufoff, gbase, voff) do { _Pragma("unroll") for (int _i = 0; _i < 2; ++_i) \
;         __builtin_amdgcn_global_load_lds((const unsigned*)((const char*)(gbase) + (voff)[_i]), (PG8_LAS unsigned*)(lds + (bufoff) + ldsw + _i * 8192), 16, 0, 0); } while (0)
; #define PG8_BAR __builtin_amdgcn_s_barrier()
; template <class Epi, class Sched, bool ALIGN_EPI = false, bool SP2 = false>
; __device__ __forceinline__ void gemm_phase(PG8_LAS unsigned char* lds, const Gemm g, const Sched S, const Epi E) {
;     ...
;     const int tid = tid_o, wid = __builtin_amdgcn_readfirstlane(tid >> 6), lane = tid & 63, wr = wid >> 2, wc = wid & 3, fr = lane & 15, fq = lane >> 4;
;     const int K = g.K, nt = K / BK;
;     unsigned voffA[2], voffB[2];
; #pragma unroll
;     for (int i = 0; i < 2; ++i) { int R, C; stage_rc(tid * 16 + i * 8192, R, C); const int Rb = Epi::PERM ? ((R & ~31) + perm32(R & 31)) : R;
;         voffA[i] = (unsigned)(R * K + C) * 2u; voffB[i] = (unsigned)(Rb * K + C) * 2u; }
;     ...
;     const char* cA = (const char*)g.A + (size_t)cur.pm * tstep; const char* cB = (const char*)g.Bt + (size_t)cur.pn * tstep;
;     S.a_ready(cur);
;     if constexpr (SP2) {
;         PG8_STAGE(PG8_SB(0, 0), cB, voffB); PG8_STAGE(PG8_SB(0, 1), cB + hstep, voffB); PG8_STAGE(PG8_SA(0, 0), cA, voffA); PG8_STAGE(PG8_SA(0, 1), cA + hstep, voffA);
;         if (wr == 1) PG8_BAR;
.LBB0_640:
	s_cmp_ge_i32 s4, s92
	s_cselect_b64 s[0:1], -1, 0
	s_and_b64 s[4:5], s[0:1], s[6:7]
	s_andn2_b64 vcc, exec, s[4:5]
	s_cbranch_vccnz .LBB0_661
	v_readlane_b32 s4, v253, 22
	v_mov_b32_e32 v0, v204
	v_mov_b32_e32 v3, v204
	v_readlane_b32 s5, v253, 23
	s_andn2_b64 vcc, exec, s[4:5]
	v_readfirstlane_b32 s4, v3
	s_cbranch_vccnz .LBB0_661
	v_lshlrev_b32_e32 v0, 4, v3
	v_add_u32_e32 v4, 0x2000, v0
	v_ashrrev_i32_e32 v2, 31, v4
	v_lshrrev_b32_e32 v2, 22, v2
	v_add_u32_e32 v2, v4, v2
	v_ashrrev_i32_e32 v2, 10, v2
	v_mul_i32_i24_e32 v5, 0x400, v2
	v_sub_u32_e32 v4, v4, v5
	v_lshrrev_b32_e32 v5, 4, v4
	v_bitop3_b32 v6, v5, v4, 32 bitop3:0x6c
	v_ashrrev_i32_e32 v4, 31, v6
	v_lshrrev_b32_e32 v4, 26, v4
	v_add_u32_e32 v7, v6, v4
	v_ashrrev_i32_e32 v4, 6, v7
	v_and_b32_e32 v7, 0xc0, v7
	v_lshlrev_b32_e32 v5, 3, v2
	v_sub_u32_e32 v6, v6, v7
	v_bfe_i32 v7, v3, 27, 1
	v_and_b32_e32 v5, 0x1ffff0, v5
	v_lshrrev_b32_e32 v7, 22, v7
	v_add_u32_e32 v8, v4, v5
	v_lshlrev_b32_e32 v5, 5, v2
	v_add_u32_e32 v7, v0, v7
	v_and_b32_e32 v5, 32, v5
	v_ashrrev_i16_sdwa v6, v208, sext(v6) dst_sel:DWORD dst_unused:UNUSED_PAD src0_sel:DWORD src1_sel:BYTE_0
	v_and_b32_e32 v7, 0xfffffc00, v7
	v_lshl_or_b32 v8, v8, 10, v5
	v_bfe_i32 v6, v6, 0, 16
	v_sub_u32_e32 v0, v0, v7
	s_waitcnt vmcnt(0)
	v_add_lshl_u32 v130, v8, v6, 1
	v_lshrrev_b32_e32 v7, 4, v0
	v_ashrrev_i32_e32 v8, 31, v3
	v_bitop3_b32 v0, v7, v0, 32 bitop3:0x6c
	v_lshrrev_b32_e32 v8, 26, v8
	v_ashrrev_i32_e32 v7, 31, v0
	v_add_u32_e32 v8, v3, v8
	v_lshrrev_b32_e32 v7, 26, v7
	v_ashrrev_i32_e32 v8, 6, v8
	v_add_u32_e32 v10, v0, v7
	v_lshlrev_b32_e32 v9, 3, v8
	v_ashrrev_i32_e32 v7, 6, v10
	v_and_b32_e32 v9, 0x1ffff0, v9
	v_and_b32_e32 v10, 0xc0, v10
	s_ashr_i32 s5, s4, 6
	v_add_u32_e32 v11, v7, v9
	v_lshlrev_b32_e32 v9, 5, v8
	v_sub_u32_e32 v0, v0, v10
	s_lshl_b32 s16, s5, 10
	v_and_b32_e32 v9, 32, v9
	v_ashrrev_i16_sdwa v0, v208, sext(v0) dst_sel:DWORD dst_unused:UNUSED_PAD src0_sel:DWORD src1_sel:BYTE_0
	v_lshl_or_b32 v11, v11, 10, v9
	v_bfe_i32 v10, v0, 0, 16
	s_add_i32 s21, s16, 0
	v_readlane_b32 s6, v254, 1
	v_add_lshl_u32 v0, v11, v10, 1
	s_add_i32 m0, s21, 0x10000
	v_readlane_b32 s7, v254, 2
	s_add_i32 s22, s21, 0x2000
	s_add_i32 s47, s21, 0x4000
	s_add_i32 s62, s21, 0x6000
	s_ashr_i32 s8, s4, 8
	s_nop 0
	global_load_lds_dwordx4 v0, s[6:7]
	s_add_i32 m0, s21, 0x12000
	s_nop 0
	global_load_lds_dwordx4 v130, s[6:7]
	v_readlane_b32 s6, v253, 57
	s_add_i32 m0, s21, 0x14000
	v_readlane_b32 s7, v253, 58
	s_nop 4
	global_load_lds_dwordx4 v0, s[6:7]
	s_add_i32 m0, s21, 0x16000
	s_cmp_eq_u32 s8, 1
	global_load_lds_dwordx4 v130, s[6:7]
	v_readlane_b32 s6, v253, 61
	s_mov_b32 m0, s21
	v_readlane_b32 s7, v253, 62
	s_nop 4
	global_load_lds_dwordx4 v0, s[6:7]
	s_mov_b32 m0, s22
	s_nop 0
	global_load_lds_dwordx4 v130, s[6:7]
	v_readlane_b32 s6, v253, 63
	s_mov_b32 m0, s47
	v_readlane_b32 s7, v254, 0
	s_nop 4
	global_load_lds_dwordx4 v0, s[6:7]
	s_mov_b32 m0, s62
	s_nop 0
	global_load_lds_dwordx4 v130, s[6:7]
	s_cselect_b64 s[6:7], -1, 0
	s_cmp_lg_u32 s8, 1
	s_cbranch_scc1 .LBB0_644
	s_barrier
	s_setprio 1

; #define PG8_STAGE(bufoff, gbase, voff) do { _Pragma("unroll") for (int _i = 0; _i < 2; ++_i) \
;         __builtin_amdgcn_global_load_lds((const unsigned*)((const char*)(gbase) + (voff)[_i]), (PG8_LAS unsigned*)(lds + (bufoff) + ldsw + _i * 8192), 16, 0, 0); } while (0)
; #define PG8_BAR __builtin_amdgcn_s_barrier()
; template <class Epi, class Sched, bool ALIGN_EPI = false, bool SP2 = false>
; __device__ __forceinline__ void gemm_phase(PG8_LAS unsigned char* lds, const Gemm g, const Sched S, const Epi E) {
;     ...
;     const int tid = tid_o, wid = __builtin_amdgcn_readfirstlane(tid >> 6), lane = tid & 63, wr = wid >> 2, wc = wid & 3, fr = lane & 15, fq = lane >> 4;
;     const int K = g.K, nt = K / BK;
;     unsigned voffA[2], voffB[2];
; #pragma unroll
;     for (int i = 0; i < 2; ++i) { int R, C; stage_rc(tid * 16 + i * 8192, R, C); const int Rb = Epi::PERM ? ((R & ~31) + perm32(R & 31)) : R;
;         voffA[i] = (unsigned)(R * K + C) * 2u; voffB[i] = (unsigned)(Rb * K + C) * 2u; }
;     ...
;     const char* cA = (const char*)g.A + (size_t)cur.pm * tstep; const char* cB = (const char*)g.Bt + (size_t)cur.pn * tstep;
;     S.a_ready(cur);
;     if constexpr (SP2) {
;         PG8_STAGE(PG8_SB(0, 0), cB, voffB); PG8_STAGE(PG8_SB(0, 1), cB + hstep, voffB); PG8_STAGE(PG8_SA(0, 0), cA, voffA); PG8_STAGE(PG8_SA(0, 1), cA + hstep, voffA);
;         if (wr == 1) PG8_BAR;
.LBB0_715:
	s_and_b64 vcc, exec, s[0:1]
	s_cbranch_vccz .LBB0_2135
	s_and_b64 vcc, exec, s[38:39]
	s_cbranch_vccnz .LBB0_797
	v_readlane_b32 s0, v253, 38
	v_mov_b32_e32 v0, v204
	v_mov_b32_e32 v3, v204
	v_readlane_b32 s1, v253, 39
	s_andn2_b64 vcc, exec, s[0:1]
	v_readfirstlane_b32 s4, v3
	s_cbranch_vccnz .LBB0_797
	v_lshlrev_b32_e32 v0, 4, v3
	v_add_u32_e32 v4, 0x2000, v0
	v_ashrrev_i32_e32 v2, 31, v4
	v_lshrrev_b32_e32 v2, 22, v2
	v_add_u32_e32 v2, v4, v2
	v_ashrrev_i32_e32 v2, 10, v2
	v_lshlrev_b32_e32 v5, 5, v2
	v_and_b32_e32 v6, 32, v5
	v_mul_i32_i24_e32 v5, 0x400, v2
	v_sub_u32_e32 v4, v4, v5
	v_lshrrev_b32_e32 v5, 4, v4
	v_bitop3_b32 v5, v5, v4, 32 bitop3:0x6c
	v_ashrrev_i32_e32 v4, 31, v5
	v_lshrrev_b32_e32 v4, 26, v4
	v_add_u32_e32 v7, v5, v4
	v_ashrrev_i32_e32 v4, 6, v7
	v_and_b32_e32 v7, 0xc0, v7
	v_sub_u32_e32 v5, v5, v7
	v_ashrrev_i16_sdwa v5, v208, sext(v5) dst_sel:DWORD dst_unused:UNUSED_PAD src0_sel:DWORD src1_sel:BYTE_0
	v_lshlrev_b32_e32 v7, 3, v2
	v_bfe_i32 v5, v5, 0, 16
	v_and_b32_e32 v7, 0xffff0, v7
	v_add_u32_e32 v6, v6, v5
	v_add_lshl_u32 v7, v4, v7, 12
	s_waitcnt vmcnt(0)
	v_lshl_add_u32 v130, v6, 1, v7
	v_ashrrev_i32_e32 v6, 31, v3
	v_lshrrev_b32_e32 v6, 26, v6
	v_add_u32_e32 v6, v3, v6
	v_ashrrev_i32_e32 v6, 6, v6
	v_lshlrev_b32_e32 v7, 5, v6
	v_and_b32_e32 v9, 32, v7
	v_bfe_i32 v7, v3, 27, 1
	v_lshrrev_b32_e32 v7, 22, v7
	v_add_u32_e32 v7, v0, v7
	v_and_b32_e32 v7, 0xfffffc00, v7
	v_sub_u32_e32 v0, v0, v7
	v_lshrrev_b32_e32 v7, 4, v0
	v_bitop3_b32 v0, v7, v0, 32 bitop3:0x6c
	v_ashrrev_i32_e32 v7, 31, v0
	v_lshrrev_b32_e32 v7, 26, v7
	v_add_u32_e32 v8, v0, v7
	v_ashrrev_i32_e32 v7, 6, v8
	v_and_b32_e32 v8, 0xc0, v8
	v_sub_u32_e32 v0, v0, v8
	v_ashrrev_i16_sdwa v0, v208, sext(v0) dst_sel:DWORD dst_unused:UNUSED_PAD src0_sel:DWORD src1_sel:BYTE_0
	v_bfe_i32 v8, v0, 0, 16
	s_ashr_i32 s5, s4, 6
	v_add_u32_e32 v0, v9, v8
	v_lshlrev_b32_e32 v9, 3, v6
	s_lshl_b32 s16, s5, 10
	v_and_b32_e32 v9, 0xffff0, v9
	v_add_lshl_u32 v9, v7, v9, 12
	s_add_i32 s21, s16, 0
	v_readlane_b32 s0, v254, 46
	v_lshl_add_u32 v0, v0, 1, v9
	s_add_i32 m0, s21, 0x10000
	v_readlane_b32 s1, v254, 47
	s_add_i32 s22, s21, 0x2000
	s_add_i32 s47, s21, 0x4000
	s_add_i32 s62, s21, 0x6000
	s_ashr_i32 s8, s4, 8
	s_nop 0
	global_load_lds_dwordx4 v0, s[0:1]
	s_add_i32 m0, s21, 0x12000
	s_nop 0
	global_load_lds_dwordx4 v130, s[0:1]
	v_readlane_b32 s0, v254, 40
	s_add_i32 m0, s21, 0x14000
	v_readlane_b32 s1, v254, 41
	s_nop 4
	global_load_lds_dwordx4 v0, s[0:1]
	s_add_i32 m0, s21, 0x16000
	s_cmp_eq_u32 s8, 1
	global_load_lds_dwordx4 v130, s[0:1]
	v_readlane_b32 s0, v254, 42
	s_mov_b32 m0, s21
	v_readlane_b32 s1, v254, 43
	s_nop 4
	global_load_lds_dwordx4 v0, s[0:1]
	s_mov_b32 m0, s22
	s_nop 0
	global_load_lds_dwordx4 v130, s[0:1]
	v_readlane_b32 s0, v254, 44
	s_mov_b32 m0, s47
	v_readlane_b32 s1, v254, 45
	s_nop 4
	global_load_lds_dwordx4 v0, s[0:1]
	s_mov_b32 m0, s62
	s_nop 0
	global_load_lds_dwordx4 v130, s[0:1]
	s_cselect_b64 s[0:1], -1, 0
	s_cmp_lg_u32 s8, 1
	s_cbranch_scc1 .LBB0_720
	s_barrier
	s_setprio 1

; #define PG8_STAGE(bufoff, gbase, voff) do { _Pragma("unroll") for (int _i = 0; _i < 2; ++_i) \
;         __builtin_amdgcn_global_load_lds((const unsigned*)((const char*)(gbase) + (voff)[_i]), (PG8_LAS unsigned*)(lds + (bufoff) + ldsw + _i * 8192), 16, 0, 0); } while (0)
; #define PG8_BAR __builtin_amdgcn_s_barrier()
; template <class Epi, class Sched, bool ALIGN_EPI = false, bool SP2 = false>
; __device__ __forceinline__ void gemm_phase(PG8_LAS unsigned char* lds, const Gemm g, const Sched S, const Epi E) {
;     ...
;     const int tid = tid_o, wid = __builtin_amdgcn_readfirstlane(tid >> 6), lane = tid & 63, wr = wid >> 2, wc = wid & 3, fr = lane & 15, fq = lane >> 4;
;     const int K = g.K, nt = K / BK;
;     unsigned voffA[2], voffB[2];
; #pragma unroll
;     for (int i = 0; i < 2; ++i) { int R, C; stage_rc(tid * 16 + i * 8192, R, C); const int Rb = Epi::PERM ? ((R & ~31) + perm32(R & 31)) : R;
;         voffA[i] = (unsigned)(R * K + C) * 2u; voffB[i] = (unsigned)(Rb * K + C) * 2u; }
;     ...
;     const char* cA = (const char*)g.A + (size_t)cur.pm * tstep; const char* cB = (const char*)g.Bt + (size_t)cur.pn * tstep;
;     S.a_ready(cur);
;     if constexpr (SP2) {
;         PG8_STAGE(PG8_SB(0, 0), cB, voffB); PG8_STAGE(PG8_SB(0, 1), cB + hstep, voffB); PG8_STAGE(PG8_SA(0, 0), cA, voffA); PG8_STAGE(PG8_SA(0, 1), cA + hstep, voffA);
;         if (wr == 1) PG8_BAR;
.LBB0_909:
	s_cmp_ge_i32 s4, s92
	s_cselect_b64 s[0:1], -1, 0
	s_and_b64 s[4:5], s[0:1], s[38:39]
	s_andn2_b64 vcc, exec, s[4:5]
	s_cbranch_vccnz .LBB0_929
	v_readlane_b32 s4, v254, 50
	v_mov_b32_e32 v0, v204
	v_mov_b32_e32 v3, v204
	v_readlane_b32 s5, v254, 51
	s_andn2_b64 vcc, exec, s[4:5]
	v_readfirstlane_b32 s4, v3
	s_cbranch_vccnz .LBB0_929
	v_lshlrev_b32_e32 v0, 4, v3
	v_add_u32_e32 v4, 0x2000, v0
	v_ashrrev_i32_e32 v2, 31, v4
	v_lshrrev_b32_e32 v2, 22, v2
	v_add_u32_e32 v2, v4, v2
	v_ashrrev_i32_e32 v2, 10, v2
	v_mul_i32_i24_e32 v5, 0x400, v2
	v_sub_u32_e32 v4, v4, v5
	v_lshrrev_b32_e32 v5, 4, v4
	v_bitop3_b32 v5, v5, v4, 32 bitop3:0x6c
	v_ashrrev_i32_e32 v4, 31, v5
	v_lshrrev_b32_e32 v4, 26, v4
	v_add_u32_e32 v6, v5, v4
	v_lshlrev_b32_e32 v7, 3, v2
	v_ashrrev_i32_e32 v4, 6, v6
	v_and_b32_e32 v7, -16, v7
	v_add_u32_e32 v7, v4, v7
	v_and_b32_e32 v8, 3, v4
	s_mov_b32 s8, 0x3fffe0
	v_lshrrev_b32_e32 v9, 2, v7
	v_lshlrev_b32_e32 v10, 1, v7
	v_and_b32_e32 v6, 0xc0, v6
	v_and_or_b32 v8, v7, s8, v8
	v_and_b32_e32 v9, 4, v9
	v_and_b32_e32 v10, 24, v10
	v_sub_u32_e32 v5, v5, v6
	v_or3_b32 v8, v8, v9, v10
	v_lshlrev_b32_e32 v9, 5, v2
	v_ashrrev_i16_sdwa v5, v208, sext(v5) dst_sel:DWORD dst_unused:UNUSED_PAD src0_sel:DWORD src1_sel:BYTE_0
	v_and_b32_e32 v9, 32, v9
	v_bfe_i32 v5, v5, 0, 16
	v_add_lshl_u32 v6, v9, v5, 1
	s_waitcnt vmcnt(0)
	v_lshl_add_u32 v130, v8, 10, v6
	v_lshl_add_u32 v132, v7, 10, v6
	v_bfe_i32 v6, v3, 27, 1
	v_lshrrev_b32_e32 v6, 22, v6
	v_add_u32_e32 v6, v0, v6
	v_and_b32_e32 v6, 0xfffffc00, v6
	v_sub_u32_e32 v0, v0, v6
	v_lshrrev_b32_e32 v6, 4, v0
	v_ashrrev_i32_e32 v7, 31, v3
	v_bitop3_b32 v0, v6, v0, 32 bitop3:0x6c
	v_lshrrev_b32_e32 v7, 26, v7
	v_ashrrev_i32_e32 v6, 31, v0
	v_add_u32_e32 v7, v3, v7
	v_lshrrev_b32_e32 v6, 26, v6
	v_ashrrev_i32_e32 v7, 6, v7
	v_add_u32_e32 v8, v0, v6
	v_lshlrev_b32_e32 v9, 3, v7
	v_ashrrev_i32_e32 v6, 6, v8
	v_and_b32_e32 v9, -16, v9
	v_add_u32_e32 v9, v6, v9
	v_and_b32_e32 v10, 3, v6
	v_lshrrev_b32_e32 v11, 2, v9
	v_lshlrev_b32_e32 v12, 1, v9
	v_and_b32_e32 v8, 0xc0, v8
	v_and_or_b32 v10, v9, s8, v10
	v_and_b32_e32 v11, 4, v11
	v_and_b32_e32 v12, 24, v12
	v_sub_u32_e32 v0, v0, v8
	s_ashr_i32 s5, s4, 6
	v_or3_b32 v10, v10, v11, v12
	v_lshlrev_b32_e32 v11, 5, v7
	v_ashrrev_i16_sdwa v0, v208, sext(v0) dst_sel:DWORD dst_unused:UNUSED_PAD src0_sel:DWORD src1_sel:BYTE_0
	s_lshl_b32 s16, s5, 10
	v_and_b32_e32 v11, 32, v11
	v_bfe_i32 v8, v0, 0, 16
	v_add_lshl_u32 v11, v11, v8, 1
	s_add_i32 s21, s16, 0
	v_readlane_b32 s8, v255, 2
	v_lshl_add_u32 v0, v10, 10, v11
	s_add_i32 m0, s21, 0x10000
	v_readlane_b32 s9, v255, 3
	v_lshl_add_u32 v134, v9, 10, v11
	s_add_i32 s22, s21, 0x2000
	s_add_i32 s47, s21, 0x4000
	s_add_i32 s62, s21, 0x6000
	s_ashr_i32 s14, s4, 8
	global_load_lds_dwordx4 v0, s[8:9]
	s_add_i32 m0, s21, 0x12000
	s_nop 0
	global_load_lds_dwordx4 v130, s[8:9]
	v_readlane_b32 s8, v254, 58
	s_add_i32 m0, s21, 0x14000
	v_readlane_b32 s9, v254, 59
	s_nop 4
	global_load_lds_dwordx4 v0, s[8:9]
	s_add_i32 m0, s21, 0x16000
	s_cmp_eq_u32 s14, 1
	global_load_lds_dwordx4 v130, s[8:9]
	v_readlane_b32 s8, v254, 62
	s_mov_b32 m0, s21
	v_readlane_b32 s9, v254, 63
	s_nop 4
	global_load_lds_dwordx4 v134, s[8:9]
	s_mov_b32 m0, s22
	s_nop 0
	global_load_lds_dwordx4 v132, s[8:9]
	v_readlane_b32 s8, v255, 0
	s_mov_b32 m0, s47
	v_readlane_b32 s9, v255, 1
	s_nop 4
	global_load_lds_dwordx4 v134, s[8:9]
	s_mov_b32 m0, s62
	s_nop 0
	global_load_lds_dwordx4 v132, s[8:9]
	s_cselect_b64 s[8:9], -1, 0
	s_cmp_lg_u32 s14, 1
	s_cbranch_scc1 .LBB0_913
	s_barrier
	s_setprio 1

; #define PG8_STAGE(bufoff, gbase, voff) do { _Pragma("unroll") for (int _i = 0; _i < 2; ++_i) \
;         __builtin_amdgcn_global_load_lds((const unsigned*)((const char*)(gbase) + (voff)[_i]), (PG8_LAS unsigned*)(lds + (bufoff) + ldsw + _i * 8192), 16, 0, 0); } while (0)
; #define PG8_BAR __builtin_amdgcn_s_barrier()
; template <class Epi, class Sched, bool ALIGN_EPI = false, bool SP2 = false>
; __device__ __forceinline__ void gemm_phase(PG8_LAS unsigned char* lds, const Gemm g, const Sched S, const Epi E) {
;     ...
;     const int tid = tid_o, wid = __builtin_amdgcn_readfirstlane(tid >> 6), lane = tid & 63, wr = wid >> 2, wc = wid & 3, fr = lane & 15, fq = lane >> 4;
;     const int K = g.K, nt = K / BK;
;     unsigned voffA[2], voffB[2];
; #pragma unroll
;     for (int i = 0; i < 2; ++i) { int R, C; stage_rc(tid * 16 + i * 8192, R, C); const int Rb = Epi::PERM ? ((R & ~31) + perm32(R & 31)) : R;
;         voffA[i] = (unsigned)(R * K + C) * 2u; voffB[i] = (unsigned)(Rb * K + C) * 2u; }
;     ...
;     const char* cA = (const char*)g.A + (size_t)cur.pm * tstep; const char* cB = (const char*)g.Bt + (size_t)cur.pn * tstep;
;     S.a_ready(cur);
;     if constexpr (SP2) {
;         PG8_STAGE(PG8_SB(0, 0), cB, voffB); PG8_STAGE(PG8_SB(0, 1), cB + hstep, voffB); PG8_STAGE(PG8_SA(0, 0), cA, voffA); PG8_STAGE(PG8_SA(0, 1), cA + hstep, voffA);
;         if (wr == 1) PG8_BAR;
.LBB0_2060:
	s_cmp_ge_i32 s4, s92
	s_cselect_b64 s[0:1], -1, 0
	s_and_b64 s[4:5], s[0:1], s[8:9]
	s_andn2_b64 vcc, exec, s[4:5]
	s_cbranch_vccnz .LBB0_2081
	v_readlane_b32 s4, v253, 22
	v_mov_b32_e32 v0, v204
	v_mov_b32_e32 v3, v204
	v_readlane_b32 s5, v253, 23
	s_andn2_b64 vcc, exec, s[4:5]
	v_readfirstlane_b32 s4, v3
	s_cbranch_vccnz .LBB0_2081
	v_lshlrev_b32_e32 v0, 4, v3
	v_add_u32_e32 v4, 0x2000, v0
	v_ashrrev_i32_e32 v2, 31, v4
	v_lshrrev_b32_e32 v2, 22, v2
	v_add_u32_e32 v2, v4, v2
	v_ashrrev_i32_e32 v2, 10, v2
	v_mul_i32_i24_e32 v5, 0x400, v2
	v_sub_u32_e32 v4, v4, v5
	v_lshrrev_b32_e32 v5, 4, v4
	v_bitop3_b32 v6, v5, v4, 32 bitop3:0x6c
	v_ashrrev_i32_e32 v4, 31, v6
	v_lshrrev_b32_e32 v4, 26, v4
	v_add_u32_e32 v7, v6, v4
	v_ashrrev_i32_e32 v4, 6, v7
	v_and_b32_e32 v7, 0xc0, v7
	v_lshlrev_b32_e32 v5, 3, v2
	v_sub_u32_e32 v6, v6, v7
	v_bfe_i32 v7, v3, 27, 1
	v_and_b32_e32 v5, 0xffff0, v5
	v_lshrrev_b32_e32 v7, 22, v7
	v_add_u32_e32 v8, v4, v5
	v_lshlrev_b32_e32 v5, 5, v2
	v_add_u32_e32 v7, v0, v7
	v_and_b32_e32 v5, 32, v5
	v_ashrrev_i16_sdwa v6, v208, sext(v6) dst_sel:DWORD dst_unused:UNUSED_PAD src0_sel:DWORD src1_sel:BYTE_0
	v_and_b32_e32 v7, 0xfffffc00, v7
	v_lshl_or_b32 v8, v8, 11, v5
	v_bfe_i32 v6, v6, 0, 16
	v_sub_u32_e32 v0, v0, v7
	s_waitcnt vmcnt(0)
	v_add_lshl_u32 v130, v8, v6, 1
	v_lshrrev_b32_e32 v7, 4, v0
	v_ashrrev_i32_e32 v8, 31, v3
	v_bitop3_b32 v0, v7, v0, 32 bitop3:0x6c
	v_lshrrev_b32_e32 v8, 26, v8
	v_ashrrev_i32_e32 v7, 31, v0
	v_add_u32_e32 v8, v3, v8
	v_lshrrev_b32_e32 v7, 26, v7
	v_ashrrev_i32_e32 v8, 6, v8
	v_add_u32_e32 v10, v0, v7
	v_lshlrev_b32_e32 v9, 3, v8
	v_ashrrev_i32_e32 v7, 6, v10
	v_and_b32_e32 v9, 0xffff0, v9
	v_and_b32_e32 v10, 0xc0, v10
	s_ashr_i32 s5, s4, 6
	v_add_u32_e32 v11, v7, v9
	v_lshlrev_b32_e32 v9, 5, v8
	v_sub_u32_e32 v0, v0, v10
	s_lshl_b32 s16, s5, 10
	v_and_b32_e32 v9, 32, v9
	v_ashrrev_i16_sdwa v0, v208, sext(v0) dst_sel:DWORD dst_unused:UNUSED_PAD src0_sel:DWORD src1_sel:BYTE_0
	v_lshl_or_b32 v11, v11, 11, v9
	v_bfe_i32 v10, v0, 0, 16
	s_add_i32 s21, s16, 0
	v_readlane_b32 s8, v254, 18
	v_add_lshl_u32 v0, v11, v10, 1
	s_add_i32 m0, s21, 0x10000
	v_readlane_b32 s9, v254, 19
	s_add_i32 s22, s21, 0x2000
	s_add_i32 s47, s21, 0x4000
	s_add_i32 s62, s21, 0x6000
	s_ashr_i32 s14, s4, 8
	s_nop 0
	global_load_lds_dwordx4 v0, s[8:9]
	s_add_i32 m0, s21, 0x12000
	s_nop 0
	global_load_lds_dwordx4 v130, s[8:9]
	v_readlane_b32 s8, v254, 12
	s_add_i32 m0, s21, 0x14000
	v_readlane_b32 s9, v254, 13
	s_nop 4
	global_load_lds_dwordx4 v0, s[8:9]
	s_add_i32 m0, s21, 0x16000
	s_cmp_eq_u32 s14, 1
	global_load_lds_dwordx4 v130, s[8:9]
	v_readlane_b32 s8, v254, 14
	s_mov_b32 m0, s21
	v_readlane_b32 s9, v254, 15
	s_nop 4
	global_load_lds_dwordx4 v0, s[8:9]
	s_mov_b32 m0, s22
	s_nop 0
	global_load_lds_dwordx4 v130, s[8:9]
	v_readlane_b32 s8, v254, 16
	s_mov_b32 m0, s47
	v_readlane_b32 s9, v254, 17
	s_nop 4
	global_load_lds_dwordx4 v0, s[8:9]
	s_mov_b32 m0, s62
	s_nop 0
	global_load_lds_dwordx4 v130, s[8:9]
	s_cselect_b64 s[8:9], -1, 0
	s_cmp_lg_u32 s14, 1
	s_cbranch_scc1 .LBB0_2064
	s_barrier
	s_setprio 1
